# P1 column-tile rotation 10 -> 0 (mixer inputs first, gate tiles last)
# speedup vs baseline: 1.0096x; 1.0031x over previous
.LBB0_103:
	s_cmp_lt_i32 s82, 2
	s_cselect_b64 s[4:5], -1, 0
	s_add_u32 s6, s80, 0x1100000
	v_writelane_b32 v255, s84, 25
	s_addc_u32 s7, s81, 0
	v_writelane_b32 v255, s6, 26
	s_nop 1
	v_writelane_b32 v255, s7, 27
	s_add_u32 s6, s80, 0x1300000
	s_addc_u32 s7, s81, 0
	v_writelane_b32 v255, s6, 28
	s_nop 1
	v_writelane_b32 v255, s7, 29
	s_add_u32 s6, s80, 0x1b00000
	s_addc_u32 s7, s81, 0
	s_add_u32 s69, s80, 0x2600000
	v_writelane_b32 v255, s6, 30
	s_addc_u32 s70, s81, 0
	s_nop 0
	v_writelane_b32 v255, s7, 31
	s_add_u32 s6, s80, 0x2c00000
	s_addc_u32 s7, s81, 0
	s_add_u32 s60, s80, 0x8c00000
	s_addc_u32 s61, s81, 0
	s_add_u32 s96, s80, 0xdc00000
	s_addc_u32 s91, s81, 0
	s_add_u32 s62, s80, 0x7c00000
	v_writelane_b32 v255, s6, 32
	s_addc_u32 s63, s81, 0
	s_and_b64 s[28:29], s[4:5], s[0:1]
	v_writelane_b32 v255, s7, 33
	s_andn2_b64 vcc, exec, s[28:29]
	s_cbranch_vccnz .LBB0_220
	s_cmpk_lt_i32 s2, 0x590
	s_cselect_b64 s[4:5], -1, 0
	s_cmpk_gt_i32 s2, 0x58f
	v_readfirstlane_b32 s6, v216
	s_cbranch_scc1 .LBB0_107
	s_cmpk_gt_i32 s2, 0x57f
	s_cbranch_scc1 .LBB0_108
	s_ashr_i32 s0, s2, 31
	s_lshr_b32 s0, s0, 29
	s_add_i32 s0, s2, s0
	s_ashr_i32 s1, s0, 3
	s_and_b32 s0, s0, -8
	s_sub_i32 s0, s2, s0
	s_cmp_lt_i32 s0, 0
	s_movk_i32 s7, 0xb1
	s_cselect_b32 s7, s7, 0xb0
	s_mul_i32 s0, s0, s7
	s_add_i32 s0, s0, s1
	s_mul_hi_i32 s1, s0, 0x2e8ba2e9
	s_lshr_b32 s7, s1, 31
	s_ashr_i32 s1, s1, 5
	s_add_i32 s1, s1, s7
	s_lshl_b32 s7, s1, 3
	s_mulk_i32 s1, 0xb0
	s_sub_i32 s0, s0, s1
	s_sext_i32_i16 s1, s0
	s_bfe_u32 s1, s1, 0x3001c
	s_add_i32 s1, s0, s1
	s_bfe_u32 s8, s1, 0xd0003
	s_and_b32 s1, s1, 0xfff8
	s_sub_i32 s0, s0, s1
	s_sext_i32_i16 s0, s0
	s_add_i32 s8, s8, 0
	s_add_i32 s38, s7, s0
	s_bfe_i32 s0, s8, 0x80000
	s_mul_i32 s0, s0, 0xffbb
	s_bfe_u32 s0, s0, 0x80008
	s_add_i32 s0, s0, s8
	s_bfe_i32 s1, s0, 0x80000
	s_and_b32 s1, 0xffff, s1
	s_lshr_b32 s1, s1, 4
	s_bfe_u32 s0, s0, 0x10007
	s_add_i32 s0, s1, s0
	s_mul_i32 s0, s0, 22
	s_sub_i32 s0, s8, s0
	s_mov_b32 s59, 0
	s_sext_i32_i8 s90, s0
	s_mov_b64 s[0:1], -1
	s_andn2_b64 vcc, exec, s[4:5]
	v_lshlrev_b32_e32 v16, 2, v216
	s_cbranch_vccz .LBB0_109
	s_branch .LBB0_178

.LBB0_117:
	s_andn2_b64 vcc, exec, s[12:13]
	s_mov_b32 s69, 1
	s_cbranch_vccnz .LBB0_119
	s_ashr_i32 s5, s4, 31
	s_lshr_b32 s5, s5, 29
	s_add_i32 s5, s4, s5
	s_ashr_i32 s12, s5, 3
	s_and_b32 s5, s5, -8
	s_sub_i32 s4, s4, s5
	s_cmp_lt_i32 s4, 0
	s_movk_i32 s5, 0xb1
	s_cselect_b32 s5, s5, 0xb0
	s_mul_i32 s4, s4, s5
	s_add_i32 s4, s4, s12
	s_mul_hi_i32 s5, s4, 0x2e8ba2e9
	s_lshr_b32 s12, s5, 31
	s_ashr_i32 s5, s5, 5
	s_add_i32 s5, s5, s12
	s_lshl_b32 s12, s5, 3
	s_sub_i32 s13, 64, s12
	s_min_i32 s13, s13, 8
	s_abs_i32 s14, s13
	v_cvt_f32_u32_e32 v0, s14
	s_sub_i32 s16, 0, s14
	s_mulk_i32 s5, 0xb0
	s_sub_i32 s4, s4, s5
	v_rcp_iflag_f32_e32 v0, v0
	s_abs_i32 s5, s4
	s_xor_b32 s15, s4, s13
	s_ashr_i32 s15, s15, 31
	v_mul_f32_e32 v0, 0x4f7ffffe, v0
	v_cvt_u32_f32_e32 v0, v0
	s_mov_b32 s69, 0
	v_readfirstlane_b32 s17, v0
	s_mul_i32 s16, s16, s17
	s_mul_hi_u32 s16, s17, s16
	s_add_i32 s17, s17, s16
	s_mul_hi_u32 s16, s5, s17
	s_mul_i32 s17, s16, s14
	s_sub_i32 s5, s5, s17
	s_add_i32 s17, s16, 1
	s_sub_i32 s18, s5, s14
	s_cmp_ge_u32 s5, s14
	s_cselect_b32 s16, s17, s16
	s_cselect_b32 s5, s18, s5
	s_add_i32 s17, s16, 1
	s_cmp_ge_u32 s5, s14
	s_cselect_b32 s5, s17, s16
	s_xor_b32 s5, s5, s15
	s_sub_i32 s5, s5, s15
	s_mul_i32 s13, s5, s13
	s_sub_i32 s4, s4, s13
	s_add_i32 s5, s5, 0
	s_add_i32 s42, s12, s4
	s_sext_i32_i16 s4, s5
	s_mulk_i32 s4, 0xba3
	s_lshr_b32 s12, s4, 31
	s_lshr_b32 s4, s4, 16
	s_add_i32 s4, s4, s12
	s_mul_i32 s4, s4, 22
	s_sub_i32 s4, s5, s4
	s_sext_i32_i16 s44, s4
